# sgemm K-loops software-pipelined: 3-buffer counted vmcnt instead of vmcnt(0) per load (4 sites)
# speedup vs baseline: 1.0082x; 1.0082x over previous
.LBB0_475:
	v_lshl_add_u64 v[76:77], v[62:63], 0, s[28:29]
	v_lshl_add_u64 v[78:79], v[64:65], 0, s[28:29]
	v_add_co_u32_e32 v80, vcc, s89, v78
	s_nop 1
	v_addc_co_u32_e32 v81, vcc, 0, v79, vcc
	v_add_co_u32_e32 v82, vcc, s96, v78
	s_nop 1
	v_addc_co_u32_e32 v83, vcc, 0, v79, vcc
	v_add_co_u32_e32 v84, vcc, s71, v78
	s_nop 1
	v_addc_co_u32_e32 v85, vcc, 0, v79, vcc
	v_add_co_u32_e32 v86, vcc, s86, v78
	s_nop 1
	v_addc_co_u32_e32 v87, vcc, 0, v79, vcc
	v_add_co_u32_e32 v88, vcc, s88, v78
	s_nop 1
	v_addc_co_u32_e32 v89, vcc, 0, v79, vcc
	v_add_co_u32_e32 v90, vcc, s61, v78
	s_nop 1
	v_addc_co_u32_e32 v91, vcc, 0, v79, vcc
	v_add_co_u32_e32 v92, vcc, s65, v78
	s_nop 1
	v_addc_co_u32_e32 v93, vcc, 0, v79, vcc
	v_add_co_u32_e32 v78, vcc, s64, v78
	s_nop 1
	v_addc_co_u32_e32 v79, vcc, 0, v79, vcc
	global_load_dwordx4 v[118:121], v[76:77], off
	global_load_dwordx4 v[122:125], v[80:81], off
	global_load_dwordx4 v[126:129], v[82:83], off
	global_load_dwordx4 v[130:133], v[84:85], off
	global_load_dwordx4 v[134:137], v[86:87], off
	global_load_dwordx4 v[138:141], v[88:89], off
	global_load_dwordx4 v[142:145], v[90:91], off
	global_load_dwordx4 v[146:149], v[92:93], off
	global_load_dwordx4 v[150:153], v[78:79], off
	global_load_dwordx4 v[154:157], v[76:77], off offset:64
	global_load_dwordx4 v[158:161], v[80:81], off offset:64
	global_load_dwordx4 v[162:165], v[82:83], off offset:64
	global_load_dwordx4 v[166:169], v[84:85], off offset:64
	global_load_dwordx4 v[182:185], v[86:87], off offset:64
	global_load_dwordx4 v[186:189], v[88:89], off offset:64
	global_load_dwordx4 v[190:193], v[90:91], off offset:64
	global_load_dwordx4 v[194:197], v[92:93], off offset:64
	global_load_dwordx4 v[202:205], v[78:79], off offset:64
	global_load_dwordx4 v[206:209], v[76:77], off offset:128
	global_load_dwordx4 v[210:213], v[80:81], off offset:128
	global_load_dwordx4 v[214:217], v[82:83], off offset:128
	global_load_dwordx4 v[220:223], v[84:85], off offset:128
	global_load_dwordx4 v[224:227], v[86:87], off offset:128
	global_load_dwordx4 v[228:231], v[88:89], off offset:128
	global_load_dwordx4 v[232:235], v[90:91], off offset:128
	global_load_dwordx4 v[244:247], v[92:93], off offset:128
	global_load_dwordx4 v[248:251], v[78:79], off offset:128
	s_waitcnt vmcnt(18)
	v_mfma_f32_16x16x32_bf16 v[36:39], v[118:121], v[122:125], v[36:39]
	v_mfma_f32_16x16x32_bf16 v[32:35], v[118:121], v[126:129], v[32:35]
	v_mfma_f32_16x16x32_bf16 v[28:31], v[118:121], v[130:133], v[28:31]
	v_mfma_f32_16x16x32_bf16 v[24:27], v[118:121], v[134:137], v[24:27]
	v_mfma_f32_16x16x32_bf16 v[20:23], v[118:121], v[138:141], v[20:23]
	v_mfma_f32_16x16x32_bf16 v[16:19], v[118:121], v[142:145], v[16:19]
	v_mfma_f32_16x16x32_bf16 v[12:15], v[118:121], v[146:149], v[12:15]
	v_mfma_f32_16x16x32_bf16 v[8:11], v[118:121], v[150:153], v[8:11]
	global_load_dwordx4 v[118:121], v[76:77], off offset:192
	global_load_dwordx4 v[122:125], v[80:81], off offset:192
	global_load_dwordx4 v[126:129], v[82:83], off offset:192
	global_load_dwordx4 v[130:133], v[84:85], off offset:192
	global_load_dwordx4 v[134:137], v[86:87], off offset:192
	global_load_dwordx4 v[138:141], v[88:89], off offset:192
	global_load_dwordx4 v[142:145], v[90:91], off offset:192
	global_load_dwordx4 v[146:149], v[92:93], off offset:192
	global_load_dwordx4 v[150:153], v[78:79], off offset:192
	s_waitcnt vmcnt(18)
	v_mfma_f32_16x16x32_bf16 v[36:39], v[154:157], v[158:161], v[36:39]
	v_mfma_f32_16x16x32_bf16 v[32:35], v[154:157], v[162:165], v[32:35]
	v_mfma_f32_16x16x32_bf16 v[28:31], v[154:157], v[166:169], v[28:31]
	v_mfma_f32_16x16x32_bf16 v[24:27], v[154:157], v[182:185], v[24:27]
	v_mfma_f32_16x16x32_bf16 v[20:23], v[154:157], v[186:189], v[20:23]
	v_mfma_f32_16x16x32_bf16 v[16:19], v[154:157], v[190:193], v[16:19]
	v_mfma_f32_16x16x32_bf16 v[12:15], v[154:157], v[194:197], v[12:15]
	v_mfma_f32_16x16x32_bf16 v[8:11], v[154:157], v[202:205], v[8:11]
	s_waitcnt vmcnt(9)
	v_mfma_f32_16x16x32_bf16 v[36:39], v[206:209], v[210:213], v[36:39]
	v_mfma_f32_16x16x32_bf16 v[32:35], v[206:209], v[214:217], v[32:35]
	v_mfma_f32_16x16x32_bf16 v[28:31], v[206:209], v[220:223], v[28:31]
	v_mfma_f32_16x16x32_bf16 v[24:27], v[206:209], v[224:227], v[24:27]
	v_mfma_f32_16x16x32_bf16 v[20:23], v[206:209], v[228:231], v[20:23]
	v_mfma_f32_16x16x32_bf16 v[16:19], v[206:209], v[232:235], v[16:19]
	v_mfma_f32_16x16x32_bf16 v[12:15], v[206:209], v[244:247], v[12:15]
	v_mfma_f32_16x16x32_bf16 v[8:11], v[206:209], v[248:251], v[8:11]
	s_waitcnt vmcnt(0)
	v_mfma_f32_16x16x32_bf16 v[36:39], v[118:121], v[122:125], v[36:39]
	v_mfma_f32_16x16x32_bf16 v[32:35], v[118:121], v[126:129], v[32:35]
	v_mfma_f32_16x16x32_bf16 v[28:31], v[118:121], v[130:133], v[28:31]
	v_mfma_f32_16x16x32_bf16 v[24:27], v[118:121], v[134:137], v[24:27]
	v_mfma_f32_16x16x32_bf16 v[20:23], v[118:121], v[138:141], v[20:23]
	v_mfma_f32_16x16x32_bf16 v[16:19], v[118:121], v[142:145], v[16:19]
	v_mfma_f32_16x16x32_bf16 v[12:15], v[118:121], v[146:149], v[12:15]
	v_mfma_f32_16x16x32_bf16 v[8:11], v[118:121], v[150:153], v[8:11]
	s_nop 4
	v_add_u32_e32 v55, s20, v61
	ds_write_b128 v55, v[36:39]
	ds_write_b128 v55, v[32:35] offset:1024
	ds_write_b128 v55, v[28:31] offset:2048
	ds_write_b128 v55, v[24:27] offset:3072
	ds_write_b128 v55, v[20:23] offset:4096
	ds_write_b128 v55, v[16:19] offset:5120
	ds_write_b128 v55, v[12:15] offset:6144
	ds_write_b128 v55, v[8:11] offset:7168
	v_add_u32_e32 v24, s21, v61
	s_waitcnt lgkmcnt(0)
	s_barrier
	ds_read_b128 v[8:11], v24
	ds_read_b128 v[12:15], v24 offset:8192
	ds_read_b128 v[16:19], v24 offset:16384
	v_xor_b32_e32 v7, 0x80000000, v7
	v_xor_b32_e32 v6, 0x80000000, v6
	s_waitcnt lgkmcnt(2)
	v_pk_add_f32 v[10:11], v[10:11], 0 op_sel_hi:[1,0]
	v_pk_add_f32 v[20:21], v[8:9], 0 op_sel_hi:[1,0]
	s_waitcnt lgkmcnt(1)
	v_pk_add_f32 v[14:15], v[10:11], v[14:15]
	ds_read_b128 v[8:11], v24 offset:24576
	v_pk_add_f32 v[20:21], v[20:21], v[12:13]
	s_waitcnt lgkmcnt(1)
	v_pk_add_f32 v[18:19], v[14:15], v[18:19]
	ds_read_b128 v[12:15], v24 offset:32768
	v_pk_add_f32 v[16:17], v[20:21], v[16:17]
	s_waitcnt lgkmcnt(1)
	v_pk_add_f32 v[18:19], v[18:19], v[10:11]
	v_pk_add_f32 v[20:21], v[16:17], v[8:9]
	ds_read_b128 v[8:11], v24 offset:40960
	s_waitcnt lgkmcnt(1)
	v_pk_add_f32 v[22:23], v[18:19], v[14:15]
	ds_read_b128 v[14:17], v24 offset:49152
	v_pk_add_f32 v[12:13], v[20:21], v[12:13]
	ds_read_b128 v[18:21], v24 offset:57344
	s_waitcnt lgkmcnt(2)
	v_pk_add_f32 v[10:11], v[22:23], v[10:11]
	v_pk_add_f32 v[8:9], v[12:13], v[8:9]
	s_waitcnt lgkmcnt(1)
	v_pk_add_f32 v[10:11], v[10:11], v[16:17]
	v_pk_add_f32 v[8:9], v[8:9], v[14:15]
	s_waitcnt lgkmcnt(0)
	v_pk_add_f32 v[10:11], v[10:11], v[20:21]
	v_pk_add_f32 v[8:9], v[8:9], v[18:19]
	v_pk_fma_f32 v[6:7], v[6:7], v[58:59], v[10:11] op_sel_hi:[1,0,1]
	v_pk_fma_f32 v[4:5], v[4:5], v[58:59], v[8:9] op_sel_hi:[1,0,1] neg_lo:[1,0,0] neg_hi:[1,0,0]
	v_pk_fma_f32 v[2:3], v[60:61], v[6:7], v[2:3] op_sel_hi:[0,1,1]
	v_pk_fma_f32 v[0:1], v[60:61], v[4:5], v[0:1] op_sel_hi:[0,1,1]
	v_cndmask_b32_e64 v3, v3, v11, s[22:23]
	v_cndmask_b32_e64 v2, v2, v10, s[22:23]
	v_cndmask_b32_e64 v1, v1, v9, s[22:23]
	v_cndmask_b32_e64 v0, v0, v8, s[22:23]
	v_cmp_lt_i32_e32 vcc, s19, v56
	s_and_saveexec_b64 s[10:11], vcc
	s_xor_b64 s[10:11], exec, s[10:11]
	s_cbranch_execz .LBB0_485
	s_cmpk_gt_u32 s4, 0x2ff
	s_mov_b64 s[12:13], -1
	s_cbranch_scc0 .LBB0_479
	v_lshl_add_u64 v[4:5], v[56:57], 1, v[42:43]
	v_add_co_u32_e32 v4, vcc, 0x82af000, v4
	v_cvt_pk_bf16_f32 v6, v0, v1
	v_cvt_pk_bf16_f32 v7, v2, v3
	s_mov_b64 s[12:13], 0
	s_nop 0
	v_addc_co_u32_e32 v5, vcc, 0, v5, vcc
	global_store_dwordx2 v[4:5], v[6:7], off offset:2560

.LBB0_1096:
	v_lshl_add_u64 v[66:67], v[60:61], 0, s[42:43]
	s_mov_b32 s11, 0x600000
	v_add_co_u32_e32 v74, vcc, s11, v66
	v_lshl_add_u64 v[76:77], v[62:63], 0, s[42:43]
	s_nop 1
	v_addc_co_u32_e32 v75, vcc, 0, v67, vcc
	v_add_co_u32_e32 v78, vcc, s52, v76
	s_mov_b32 s11, 0x6a48000
	s_nop 1
	v_addc_co_u32_e32 v79, vcc, 0, v77, vcc
	v_add_co_u32_e32 v80, vcc, s11, v76
	s_mov_b32 s11, 0x6a50000
	s_nop 1
	v_addc_co_u32_e32 v81, vcc, 0, v77, vcc
	v_add_co_u32_e32 v82, vcc, s11, v76
	s_mov_b32 s11, 0x6a58000
	s_nop 1
	v_addc_co_u32_e32 v83, vcc, 0, v77, vcc
	v_add_co_u32_e32 v84, vcc, s11, v76
	s_mov_b32 s11, 0x6a60000
	s_nop 1
	v_addc_co_u32_e32 v85, vcc, 0, v77, vcc
	v_add_co_u32_e32 v86, vcc, s11, v76
	s_mov_b32 s11, 0x6a68000
	s_nop 1
	v_addc_co_u32_e32 v87, vcc, 0, v77, vcc
	v_add_co_u32_e32 v88, vcc, s11, v76
	s_mov_b32 s11, 0x6a70000
	s_nop 1
	v_addc_co_u32_e32 v89, vcc, 0, v77, vcc
	v_add_co_u32_e32 v90, vcc, s11, v76
	s_mov_b32 s11, 0x6a78000
	s_nop 1
	v_addc_co_u32_e32 v91, vcc, 0, v77, vcc
	v_add_co_u32_e32 v76, vcc, s11, v76
	s_nop 1
	v_addc_co_u32_e32 v77, vcc, 0, v77, vcc
	global_load_dwordx4 v[118:121], v[74:75], off
	global_load_dwordx4 v[122:125], v[78:79], off
	global_load_dwordx4 v[126:129], v[80:81], off
	global_load_dwordx4 v[130:133], v[82:83], off
	global_load_dwordx4 v[134:137], v[84:85], off
	global_load_dwordx4 v[138:141], v[86:87], off
	global_load_dwordx4 v[142:145], v[88:89], off
	global_load_dwordx4 v[146:149], v[90:91], off
	global_load_dwordx4 v[150:153], v[76:77], off
	global_load_dwordx4 v[154:157], v[74:75], off offset:64
	global_load_dwordx4 v[158:161], v[78:79], off offset:64
	global_load_dwordx4 v[162:165], v[80:81], off offset:64
	global_load_dwordx4 v[166:169], v[82:83], off offset:64
	global_load_dwordx4 v[182:185], v[84:85], off offset:64
	global_load_dwordx4 v[186:189], v[86:87], off offset:64
	global_load_dwordx4 v[190:193], v[88:89], off offset:64
	global_load_dwordx4 v[194:197], v[90:91], off offset:64
	global_load_dwordx4 v[202:205], v[76:77], off offset:64
	global_load_dwordx4 v[206:209], v[74:75], off offset:128
	global_load_dwordx4 v[210:213], v[78:79], off offset:128
	global_load_dwordx4 v[214:217], v[80:81], off offset:128
	global_load_dwordx4 v[220:223], v[82:83], off offset:128
	global_load_dwordx4 v[224:227], v[84:85], off offset:128
	global_load_dwordx4 v[228:231], v[86:87], off offset:128
	global_load_dwordx4 v[232:235], v[88:89], off offset:128
	global_load_dwordx4 v[244:247], v[90:91], off offset:128
	global_load_dwordx4 v[248:251], v[76:77], off offset:128
	s_waitcnt vmcnt(18)
	v_mfma_f32_16x16x32_bf16 v[36:39], v[118:121], v[122:125], v[36:39]
	v_mfma_f32_16x16x32_bf16 v[32:35], v[118:121], v[126:129], v[32:35]
	v_mfma_f32_16x16x32_bf16 v[28:31], v[118:121], v[130:133], v[28:31]
	v_mfma_f32_16x16x32_bf16 v[24:27], v[118:121], v[134:137], v[24:27]
	v_mfma_f32_16x16x32_bf16 v[20:23], v[118:121], v[138:141], v[20:23]
	v_mfma_f32_16x16x32_bf16 v[16:19], v[118:121], v[142:145], v[16:19]
	v_mfma_f32_16x16x32_bf16 v[12:15], v[118:121], v[146:149], v[12:15]
	v_mfma_f32_16x16x32_bf16 v[8:11], v[118:121], v[150:153], v[8:11]
	global_load_dwordx4 v[118:121], v[74:75], off offset:192
	global_load_dwordx4 v[122:125], v[78:79], off offset:192
	global_load_dwordx4 v[126:129], v[80:81], off offset:192
	global_load_dwordx4 v[130:133], v[82:83], off offset:192
	global_load_dwordx4 v[134:137], v[84:85], off offset:192
	global_load_dwordx4 v[138:141], v[86:87], off offset:192
	global_load_dwordx4 v[142:145], v[88:89], off offset:192
	global_load_dwordx4 v[146:149], v[90:91], off offset:192
	global_load_dwordx4 v[150:153], v[76:77], off offset:192
	s_waitcnt vmcnt(18)
	v_mfma_f32_16x16x32_bf16 v[36:39], v[154:157], v[158:161], v[36:39]
	v_mfma_f32_16x16x32_bf16 v[32:35], v[154:157], v[162:165], v[32:35]
	v_mfma_f32_16x16x32_bf16 v[28:31], v[154:157], v[166:169], v[28:31]
	v_mfma_f32_16x16x32_bf16 v[24:27], v[154:157], v[182:185], v[24:27]
	v_mfma_f32_16x16x32_bf16 v[20:23], v[154:157], v[186:189], v[20:23]
	v_mfma_f32_16x16x32_bf16 v[16:19], v[154:157], v[190:193], v[16:19]
	v_mfma_f32_16x16x32_bf16 v[12:15], v[154:157], v[194:197], v[12:15]
	v_mfma_f32_16x16x32_bf16 v[8:11], v[154:157], v[202:205], v[8:11]
	s_waitcnt vmcnt(9)
	v_mfma_f32_16x16x32_bf16 v[36:39], v[206:209], v[210:213], v[36:39]
	v_mfma_f32_16x16x32_bf16 v[32:35], v[206:209], v[214:217], v[32:35]
	v_mfma_f32_16x16x32_bf16 v[28:31], v[206:209], v[220:223], v[28:31]
	v_mfma_f32_16x16x32_bf16 v[24:27], v[206:209], v[224:227], v[24:27]
	v_mfma_f32_16x16x32_bf16 v[20:23], v[206:209], v[228:231], v[20:23]
	v_mfma_f32_16x16x32_bf16 v[16:19], v[206:209], v[232:235], v[16:19]
	v_mfma_f32_16x16x32_bf16 v[12:15], v[206:209], v[244:247], v[12:15]
	v_mfma_f32_16x16x32_bf16 v[8:11], v[206:209], v[248:251], v[8:11]
	s_waitcnt vmcnt(0)
	v_mfma_f32_16x16x32_bf16 v[36:39], v[118:121], v[122:125], v[36:39]
	v_mfma_f32_16x16x32_bf16 v[32:35], v[118:121], v[126:129], v[32:35]
	v_mfma_f32_16x16x32_bf16 v[28:31], v[118:121], v[130:133], v[28:31]
	v_mfma_f32_16x16x32_bf16 v[24:27], v[118:121], v[134:137], v[24:27]
	v_mfma_f32_16x16x32_bf16 v[20:23], v[118:121], v[138:141], v[20:23]
	v_mfma_f32_16x16x32_bf16 v[16:19], v[118:121], v[142:145], v[16:19]
	v_mfma_f32_16x16x32_bf16 v[12:15], v[118:121], v[146:149], v[12:15]
	v_mfma_f32_16x16x32_bf16 v[8:11], v[118:121], v[150:153], v[8:11]
	s_nop 4
	v_add_u32_e32 v49, s4, v55
	ds_write_b128 v49, v[36:39]
	ds_write_b128 v49, v[32:35] offset:1024
	ds_write_b128 v49, v[28:31] offset:2048
	ds_write_b128 v49, v[24:27] offset:3072
	ds_write_b128 v49, v[20:23] offset:4096
	ds_write_b128 v49, v[16:19] offset:5120
	ds_write_b128 v49, v[12:15] offset:6144
	ds_write_b128 v49, v[8:11] offset:7168
	v_add_u32_e32 v24, s12, v55
	s_waitcnt lgkmcnt(0)
	s_barrier
	ds_read_b128 v[8:11], v24
	ds_read_b128 v[12:15], v24 offset:8192
	ds_read_b128 v[16:19], v24 offset:16384
	s_waitcnt lgkmcnt(2)
	v_pk_add_f32 v[10:11], v[10:11], 0 op_sel_hi:[1,0]
	v_pk_add_f32 v[20:21], v[8:9], 0 op_sel_hi:[1,0]
	s_waitcnt lgkmcnt(1)
	v_pk_add_f32 v[14:15], v[10:11], v[14:15]
	ds_read_b128 v[8:11], v24 offset:24576
	v_pk_add_f32 v[20:21], v[20:21], v[12:13]
	s_waitcnt lgkmcnt(1)
	v_pk_add_f32 v[18:19], v[14:15], v[18:19]
	ds_read_b128 v[12:15], v24 offset:32768
	v_pk_add_f32 v[16:17], v[20:21], v[16:17]
	s_waitcnt lgkmcnt(1)
	v_pk_add_f32 v[18:19], v[18:19], v[10:11]
	v_pk_add_f32 v[20:21], v[16:17], v[8:9]
	ds_read_b128 v[8:11], v24 offset:40960
	s_waitcnt lgkmcnt(1)
	v_pk_add_f32 v[22:23], v[18:19], v[14:15]
	ds_read_b128 v[14:17], v24 offset:49152
	v_pk_add_f32 v[12:13], v[20:21], v[12:13]
	ds_read_b128 v[18:21], v24 offset:57344
	s_waitcnt lgkmcnt(2)
	v_pk_add_f32 v[8:9], v[12:13], v[8:9]
	v_pk_add_f32 v[10:11], v[22:23], v[10:11]
	s_waitcnt lgkmcnt(1)
	v_pk_add_f32 v[8:9], v[8:9], v[14:15]
	v_pk_add_f32 v[10:11], v[10:11], v[16:17]
	s_waitcnt lgkmcnt(0)
	v_pk_add_f32 v[8:9], v[8:9], v[18:19]
	v_lshlrev_b32_e32 v18, 16, v59
	v_and_b32_e32 v19, 0xffff0000, v59
	v_lshlrev_b32_e32 v16, 16, v58
	v_and_b32_e32 v17, 0xffff0000, v58
	v_sub_f32_e32 v13, v19, v56
	v_sub_f32_e32 v12, v18, v56
	v_sub_f32_e32 v15, v17, v56
	v_sub_f32_e32 v14, v16, v56
	v_pk_mul_f32 v[12:13], v[54:55], v[12:13] op_sel_hi:[0,1]
	v_pk_mul_f32 v[14:15], v[54:55], v[14:15] op_sel_hi:[0,1]
	v_pk_fma_f32 v[2:3], v[2:3], v[12:13], v[6:7]
	v_pk_add_f32 v[10:11], v[10:11], v[20:21]
	v_pk_fma_f32 v[0:1], v[0:1], v[14:15], v[4:5]
	v_cndmask_b32_e64 v3, v3, v19, s[28:29]
	v_cndmask_b32_e64 v2, v2, v18, s[28:29]
	v_cndmask_b32_e64 v1, v1, v17, s[28:29]
	v_cndmask_b32_e64 v0, v0, v16, s[28:29]
	v_pk_fma_f32 v[4:5], v[2:3], s[70:71], v[10:11] op_sel_hi:[1,0,1]
	v_and_b32_e32 v2, 64, v237
	v_pk_fma_f32 v[6:7], v[0:1], s[70:71], v[8:9] op_sel_hi:[1,0,1]
	v_xor_b32_e32 v0, 16, v237
	v_add_u32_e32 v12, 64, v2
	v_cmp_lt_i32_e32 vcc, v0, v12
	v_mul_f32_e32 v1, v6, v6
	v_mul_f32_e32 v3, v7, v7
	v_cndmask_b32_e32 v0, v237, v0, vcc
	v_mul_f32_e32 v9, v4, v4
	v_mul_f32_e32 v11, v5, v5
	v_lshlrev_b32_e32 v13, 2, v0
	v_mov_b32_e32 v0, v6
	v_mov_b32_e32 v2, v7
	v_mov_b32_e32 v8, v4
	v_mov_b32_e32 v10, v5
	v_pk_add_f32 v[0:1], v[0:1], v[2:3]
	v_pk_add_f32 v[2:3], v[8:9], v[10:11]
	v_xor_b32_e32 v8, 32, v237
	v_pk_add_f32 v[0:1], v[0:1], v[2:3]
	ds_bpermute_b32 v2, v13, v0
	ds_bpermute_b32 v3, v13, v1
	v_cmp_lt_i32_e32 vcc, v8, v12
	v_cvt_pk_bf16_f32 v6, v6, v7
	v_cvt_pk_bf16_f32 v7, v4, v5
	global_store_dwordx2 v[52:53], v[6:7], off
	s_waitcnt lgkmcnt(0)
	v_pk_add_f32 v[0:1], v[0:1], v[2:3]
	v_cndmask_b32_e32 v8, v237, v8, vcc
	v_lshlrev_b32_e32 v8, 2, v8
	ds_bpermute_b32 v2, v8, v0
	ds_bpermute_b32 v3, v8, v1
	s_and_saveexec_b64 s[10:11], s[30:31]
	s_cbranch_execz .LBB0_1092
	s_lshl_b32 s16, s13, 1
	s_ashr_i32 s17, s16, 31
	v_lshl_add_u64 v[4:5], s[16:17], 2, v[44:45]
	s_waitcnt lgkmcnt(0)
	v_pk_add_f32 v[0:1], v[0:1], v[2:3]
	global_store_dwordx2 v[4:5], v[0:1], off
	s_branch .LBB0_1092

.LBB0_1271:
	v_lshl_add_u64 v[92:93], v[82:83], 0, s[28:29]
	s_mov_b32 s13, 0xa00000
	v_add_co_u32_e32 v100, vcc, s13, v92
	v_lshl_add_u64 v[102:103], v[86:87], 0, s[28:29]
	s_nop 1
	v_addc_co_u32_e32 v101, vcc, 0, v93, vcc
	v_add_co_u32_e32 v104, vcc, s89, v102
	s_nop 1
	v_addc_co_u32_e32 v105, vcc, 0, v103, vcc
	v_add_co_u32_e32 v106, vcc, s96, v102
	s_nop 1
	v_addc_co_u32_e32 v107, vcc, 0, v103, vcc
	v_add_co_u32_e32 v108, vcc, s71, v102
	s_nop 1
	v_addc_co_u32_e32 v109, vcc, 0, v103, vcc
	v_add_co_u32_e32 v110, vcc, s86, v102
	s_nop 1
	v_addc_co_u32_e32 v111, vcc, 0, v103, vcc
	v_add_co_u32_e32 v112, vcc, s88, v102
	s_nop 1
	v_addc_co_u32_e32 v113, vcc, 0, v103, vcc
	v_add_co_u32_e32 v114, vcc, s61, v102
	s_nop 1
	v_addc_co_u32_e32 v115, vcc, 0, v103, vcc
	v_add_co_u32_e32 v116, vcc, s65, v102
	s_nop 1
	v_addc_co_u32_e32 v117, vcc, 0, v103, vcc
	v_add_co_u32_e32 v102, vcc, s64, v102
	s_nop 1
	v_addc_co_u32_e32 v103, vcc, 0, v103, vcc
	global_load_dwordx4 v[118:121], v[100:101], off
	global_load_dwordx4 v[122:125], v[104:105], off
	global_load_dwordx4 v[126:129], v[106:107], off
	global_load_dwordx4 v[130:133], v[108:109], off
	global_load_dwordx4 v[134:137], v[110:111], off
	global_load_dwordx4 v[138:141], v[112:113], off
	global_load_dwordx4 v[142:145], v[114:115], off
	global_load_dwordx4 v[146:149], v[116:117], off
	global_load_dwordx4 v[150:153], v[102:103], off
	global_load_dwordx4 v[154:157], v[100:101], off offset:64
	global_load_dwordx4 v[158:161], v[104:105], off offset:64
	global_load_dwordx4 v[162:165], v[106:107], off offset:64
	global_load_dwordx4 v[166:169], v[108:109], off offset:64
	global_load_dwordx4 v[182:185], v[110:111], off offset:64
	global_load_dwordx4 v[186:189], v[112:113], off offset:64
	global_load_dwordx4 v[190:193], v[114:115], off offset:64
	global_load_dwordx4 v[194:197], v[116:117], off offset:64
	global_load_dwordx4 v[202:205], v[102:103], off offset:64
	global_load_dwordx4 v[206:209], v[100:101], off offset:128
	global_load_dwordx4 v[210:213], v[104:105], off offset:128
	global_load_dwordx4 v[214:217], v[106:107], off offset:128
	global_load_dwordx4 v[220:223], v[108:109], off offset:128
	global_load_dwordx4 v[224:227], v[110:111], off offset:128
	global_load_dwordx4 v[228:231], v[112:113], off offset:128
	global_load_dwordx4 v[232:235], v[114:115], off offset:128
	global_load_dwordx4 v[244:247], v[116:117], off offset:128
	global_load_dwordx4 v[248:251], v[102:103], off offset:128
	s_waitcnt vmcnt(18)
	v_mfma_f32_16x16x32_bf16 v[64:67], v[118:121], v[122:125], v[64:67]
	v_mfma_f32_16x16x32_bf16 v[60:63], v[118:121], v[126:129], v[60:63]
	v_mfma_f32_16x16x32_bf16 v[56:59], v[118:121], v[130:133], v[56:59]
	v_mfma_f32_16x16x32_bf16 v[52:55], v[118:121], v[134:137], v[52:55]
	v_mfma_f32_16x16x32_bf16 v[48:51], v[118:121], v[138:141], v[48:51]
	v_mfma_f32_16x16x32_bf16 v[44:47], v[118:121], v[142:145], v[44:47]
	v_mfma_f32_16x16x32_bf16 v[68:71], v[118:121], v[146:149], v[68:71]
	v_mfma_f32_16x16x32_bf16 v[28:31], v[118:121], v[150:153], v[28:31]
	global_load_dwordx4 v[118:121], v[100:101], off offset:192
	global_load_dwordx4 v[122:125], v[104:105], off offset:192
	global_load_dwordx4 v[126:129], v[106:107], off offset:192
	global_load_dwordx4 v[130:133], v[108:109], off offset:192
	global_load_dwordx4 v[134:137], v[110:111], off offset:192
	global_load_dwordx4 v[138:141], v[112:113], off offset:192
	global_load_dwordx4 v[142:145], v[114:115], off offset:192
	global_load_dwordx4 v[146:149], v[116:117], off offset:192
	global_load_dwordx4 v[150:153], v[102:103], off offset:192
	s_waitcnt vmcnt(18)
	v_mfma_f32_16x16x32_bf16 v[64:67], v[154:157], v[158:161], v[64:67]
	v_mfma_f32_16x16x32_bf16 v[60:63], v[154:157], v[162:165], v[60:63]
	v_mfma_f32_16x16x32_bf16 v[56:59], v[154:157], v[166:169], v[56:59]
	v_mfma_f32_16x16x32_bf16 v[52:55], v[154:157], v[182:185], v[52:55]
	v_mfma_f32_16x16x32_bf16 v[48:51], v[154:157], v[186:189], v[48:51]
	v_mfma_f32_16x16x32_bf16 v[44:47], v[154:157], v[190:193], v[44:47]
	v_mfma_f32_16x16x32_bf16 v[68:71], v[154:157], v[194:197], v[68:71]
	v_mfma_f32_16x16x32_bf16 v[28:31], v[154:157], v[202:205], v[28:31]
	s_waitcnt vmcnt(9)
	v_mfma_f32_16x16x32_bf16 v[64:67], v[206:209], v[210:213], v[64:67]
	v_mfma_f32_16x16x32_bf16 v[60:63], v[206:209], v[214:217], v[60:63]
	v_mfma_f32_16x16x32_bf16 v[56:59], v[206:209], v[220:223], v[56:59]
	v_mfma_f32_16x16x32_bf16 v[52:55], v[206:209], v[224:227], v[52:55]
	v_mfma_f32_16x16x32_bf16 v[48:51], v[206:209], v[228:231], v[48:51]
	v_mfma_f32_16x16x32_bf16 v[44:47], v[206:209], v[232:235], v[44:47]
	v_mfma_f32_16x16x32_bf16 v[68:71], v[206:209], v[244:247], v[68:71]
	v_mfma_f32_16x16x32_bf16 v[28:31], v[206:209], v[248:251], v[28:31]
	s_waitcnt vmcnt(0)
	v_mfma_f32_16x16x32_bf16 v[64:67], v[118:121], v[122:125], v[64:67]
	v_mfma_f32_16x16x32_bf16 v[60:63], v[118:121], v[126:129], v[60:63]
	v_mfma_f32_16x16x32_bf16 v[56:59], v[118:121], v[130:133], v[56:59]
	v_mfma_f32_16x16x32_bf16 v[52:55], v[118:121], v[134:137], v[52:55]
	v_mfma_f32_16x16x32_bf16 v[48:51], v[118:121], v[138:141], v[48:51]
	v_mfma_f32_16x16x32_bf16 v[44:47], v[118:121], v[142:145], v[44:47]
	v_mfma_f32_16x16x32_bf16 v[68:71], v[118:121], v[146:149], v[68:71]
	v_mfma_f32_16x16x32_bf16 v[28:31], v[118:121], v[150:153], v[28:31]
	s_nop 4
	v_add_f32_e32 v4, v13, v15
	v_add_f32_e32 v6, v9, v11
	v_add_f32_e32 v4, 0, v4
	v_add_f32_e32 v5, v5, v7
	v_add_f32_e32 v4, v4, v6
	v_add_f32_e32 v1, v1, v3
	v_add_f32_e32 v4, v4, v5
	v_add_f32_e32 v3, v41, v43
	v_add_f32_e32 v1, v4, v1
	v_add_f32_e32 v7, v25, v27
	v_add_f32_e32 v1, v1, v3
	v_add_f32_e32 v8, v21, v23
	v_add_f32_e32 v1, v1, v7
	v_add_f32_e32 v9, v17, v19
	v_add_f32_e32 v1, v1, v8
	v_add_f32_e32 v8, v1, v9
	v_add_u32_e32 v1, s4, v88
	v_add_u32_e32 v18, s10, v88
	ds_bpermute_b32 v9, v89, v8
	ds_write_b128 v1, v[64:67]
	ds_write_b128 v1, v[60:63] offset:1024
	ds_write_b128 v1, v[56:59] offset:2048
	ds_write_b128 v1, v[52:55] offset:3072
	ds_write_b128 v1, v[48:51] offset:4096
	ds_write_b128 v1, v[44:47] offset:5120
	ds_write_b128 v1, v[68:71] offset:6144
	ds_write_b128 v1, v[28:31] offset:7168
	s_waitcnt lgkmcnt(0)
	s_barrier
	ds_read_b128 v[4:7], v18
	v_add_f32_e32 v13, v0, v2
	ds_read_b128 v[0:3], v18 offset:8192
	v_add_f32_e32 v12, v8, v9
	ds_bpermute_b32 v15, v90, v13
	s_waitcnt lgkmcnt(2)
	v_pk_add_f32 v[10:11], v[6:7], 0 op_sel_hi:[1,0]
	ds_read_b128 v[6:9], v18 offset:16384
	v_pk_add_f32 v[16:17], v[4:5], 0 op_sel_hi:[1,0]
	s_waitcnt lgkmcnt(2)
	v_pk_add_f32 v[10:11], v[10:11], v[2:3]
	ds_read_b128 v[2:5], v18 offset:24576
	v_pk_add_f32 v[0:1], v[16:17], v[0:1]
	s_waitcnt lgkmcnt(1)
	v_pk_add_f32 v[16:17], v[10:11], v[8:9]
	ds_read_b128 v[8:11], v18 offset:32768
	v_pk_add_f32 v[0:1], v[0:1], v[6:7]
	s_waitcnt lgkmcnt(1)
	v_pk_add_f32 v[4:5], v[16:17], v[4:5]
	v_pk_add_f32 v[6:7], v[0:1], v[2:3]
	ds_read_b128 v[0:3], v18 offset:40960
	s_waitcnt lgkmcnt(1)
	v_pk_add_f32 v[10:11], v[4:5], v[10:11]
	v_pk_add_f32 v[8:9], v[6:7], v[8:9]
	ds_read_b128 v[4:7], v18 offset:49152
	ds_bpermute_b32 v14, v90, v12
	s_waitcnt lgkmcnt(2)
	v_pk_add_f32 v[10:11], v[10:11], v[2:3]
	v_pk_add_f32 v[8:9], v[8:9], v[0:1]
	ds_read_b128 v[0:3], v18 offset:57344
	s_waitcnt lgkmcnt(2)
	v_pk_add_f32 v[6:7], v[10:11], v[6:7]
	s_waitcnt lgkmcnt(1)
	v_pk_add_f32 v[10:11], v[12:13], v[14:15]
	v_pk_add_f32 v[4:5], v[8:9], v[4:5]
	v_pk_mul_f32 v[10:11], v[10:11], s[6:7] op_sel_hi:[1,0]
	s_waitcnt lgkmcnt(0)
	v_pk_add_f32 v[0:1], v[4:5], v[0:1]
	v_fma_f32 v12, -v11, v11, v10
	v_max_f32_e32 v12, 0, v12
	v_add_f32_e32 v12, 0x3727c5ac, v12
	v_mul_f32_e32 v13, 0x4b800000, v12
	v_cmp_gt_f32_e32 vcc, s14, v12
	v_pk_add_f32 v[2:3], v[6:7], v[2:3]
	v_pk_fma_f32 v[0:1], v[32:33], v[10:11], v[0:1] op_sel:[0,1,0] neg_lo:[1,0,0] neg_hi:[1,0,0]
	v_cndmask_b32_e32 v12, v12, v13, vcc
	v_rsq_f32_e32 v12, v12
	v_xor_b32_e32 v7, 0x80000000, v35
	v_xor_b32_e32 v6, 0x80000000, v34
	v_pk_fma_f32 v[2:3], v[6:7], v[10:11], v[2:3] op_sel:[0,1,0]
	v_mul_f32_e32 v4, 0x45800000, v12
	v_cndmask_b32_e32 v4, v12, v4, vcc
	v_pk_fma_f32 v[0:1], v[0:1], v[4:5], v[36:37] op_sel_hi:[1,0,1]
	v_pk_fma_f32 v[2:3], v[2:3], v[4:5], v[38:39] op_sel_hi:[1,0,1]
	v_max_f32_e32 v0, 0, v0
	v_max_f32_e32 v1, 0, v1
	s_add_i32 s11, s11, s3
	v_max_f32_e32 v2, 0, v2
	v_max_f32_e32 v3, 0, v3
	v_pk_mul_f32 v[0:1], v[0:1], v[0:1]
	v_lshl_add_u64 v[4:5], v[84:85], 1, v[74:75]
	s_cmpk_lt_i32 s11, 0x100
	v_add_u32_e32 v78, s87, v78
	v_pk_mul_f32 v[2:3], v[2:3], v[2:3]
	v_cvt_pk_bf16_f32 v0, v0, v1
	s_nop 0
	v_cvt_pk_bf16_f32 v1, v2, v3
	global_store_dwordx2 v[4:5], v[0:1], off
	s_barrier
	s_cbranch_scc1 .LBB0_1270

.LBB0_1375:
	v_lshl_add_u64 v[68:69], v[52:53], 0, s[34:35]
	s_mov_b32 s11, 0x1a00000
	v_add_co_u32_e64 v76, s[22:23], s11, v68
	v_lshl_add_u64 v[78:79], v[62:63], 0, s[34:35]
	s_nop 1
	v_addc_co_u32_e64 v77, s[22:23], 0, v69, s[22:23]
	s_mov_b32 s11, 0xea80000
	v_add_co_u32_e64 v80, s[22:23], s11, v78
	s_mov_b32 s11, 0xeaa0000
	s_nop 1
	v_addc_co_u32_e64 v81, s[22:23], 0, v79, s[22:23]
	v_add_co_u32_e64 v82, s[22:23], s11, v78
	s_mov_b32 s11, 0xeac0000
	s_nop 1
	v_addc_co_u32_e64 v83, s[22:23], 0, v79, s[22:23]
	v_add_co_u32_e64 v84, s[22:23], s11, v78
	s_mov_b32 s11, 0xeae0000
	s_nop 1
	v_addc_co_u32_e64 v85, s[22:23], 0, v79, s[22:23]
	v_add_co_u32_e64 v86, s[22:23], s11, v78
	s_mov_b32 s11, 0xeb00000
	s_nop 1
	v_addc_co_u32_e64 v87, s[22:23], 0, v79, s[22:23]
	v_add_co_u32_e64 v88, s[22:23], s11, v78
	s_mov_b32 s11, 0xeb20000
	s_nop 1
	v_addc_co_u32_e64 v89, s[22:23], 0, v79, s[22:23]
	v_add_co_u32_e64 v90, s[22:23], s11, v78
	s_mov_b32 s11, 0xeb40000
	s_nop 1
	v_addc_co_u32_e64 v91, s[22:23], 0, v79, s[22:23]
	v_add_co_u32_e64 v92, s[22:23], s11, v78
	s_mov_b32 s11, 0xeb60000
	s_nop 1
	v_addc_co_u32_e64 v93, s[22:23], 0, v79, s[22:23]
	v_add_co_u32_e64 v78, s[22:23], s11, v78
	s_nop 1
	v_addc_co_u32_e64 v79, s[22:23], 0, v79, s[22:23]
	global_load_dwordx4 v[118:121], v[76:77], off
	global_load_dwordx4 v[122:125], v[80:81], off
	global_load_dwordx4 v[126:129], v[82:83], off
	global_load_dwordx4 v[130:133], v[84:85], off
	global_load_dwordx4 v[134:137], v[86:87], off
	global_load_dwordx4 v[138:141], v[88:89], off
	global_load_dwordx4 v[142:145], v[90:91], off
	global_load_dwordx4 v[146:149], v[92:93], off
	global_load_dwordx4 v[150:153], v[78:79], off
	global_load_dwordx4 v[154:157], v[76:77], off offset:64
	global_load_dwordx4 v[158:161], v[80:81], off offset:64
	global_load_dwordx4 v[162:165], v[82:83], off offset:64
	global_load_dwordx4 v[166:169], v[84:85], off offset:64
	global_load_dwordx4 v[182:185], v[86:87], off offset:64
	global_load_dwordx4 v[186:189], v[88:89], off offset:64
	global_load_dwordx4 v[190:193], v[90:91], off offset:64
	global_load_dwordx4 v[194:197], v[92:93], off offset:64
	global_load_dwordx4 v[202:205], v[78:79], off offset:64
	global_load_dwordx4 v[206:209], v[76:77], off offset:128
	global_load_dwordx4 v[210:213], v[80:81], off offset:128
	global_load_dwordx4 v[214:217], v[82:83], off offset:128
	global_load_dwordx4 v[220:223], v[84:85], off offset:128
	global_load_dwordx4 v[224:227], v[86:87], off offset:128
	global_load_dwordx4 v[228:231], v[88:89], off offset:128
	global_load_dwordx4 v[232:235], v[90:91], off offset:128
	global_load_dwordx4 v[244:247], v[92:93], off offset:128
	global_load_dwordx4 v[248:251], v[78:79], off offset:128
	s_waitcnt vmcnt(18)
	v_mfma_f32_16x16x32_bf16 v[28:31], v[118:121], v[122:125], v[28:31]
	v_mfma_f32_16x16x32_bf16 v[24:27], v[118:121], v[126:129], v[24:27]
	v_mfma_f32_16x16x32_bf16 v[20:23], v[118:121], v[130:133], v[20:23]
	v_mfma_f32_16x16x32_bf16 v[16:19], v[118:121], v[134:137], v[16:19]
	v_mfma_f32_16x16x32_bf16 v[12:15], v[118:121], v[138:141], v[12:15]
	v_mfma_f32_16x16x32_bf16 v[32:35], v[118:121], v[142:145], v[32:35]
	v_mfma_f32_16x16x32_bf16 v[36:39], v[118:121], v[146:149], v[36:39]
	v_mfma_f32_16x16x32_bf16 v[8:11], v[118:121], v[150:153], v[8:11]
	global_load_dwordx4 v[118:121], v[76:77], off offset:192
	global_load_dwordx4 v[122:125], v[80:81], off offset:192
	global_load_dwordx4 v[126:129], v[82:83], off offset:192
	global_load_dwordx4 v[130:133], v[84:85], off offset:192
	global_load_dwordx4 v[134:137], v[86:87], off offset:192
	global_load_dwordx4 v[138:141], v[88:89], off offset:192
	global_load_dwordx4 v[142:145], v[90:91], off offset:192
	global_load_dwordx4 v[146:149], v[92:93], off offset:192
	global_load_dwordx4 v[150:153], v[78:79], off offset:192
	s_waitcnt vmcnt(18)
	v_mfma_f32_16x16x32_bf16 v[28:31], v[154:157], v[158:161], v[28:31]
	v_mfma_f32_16x16x32_bf16 v[24:27], v[154:157], v[162:165], v[24:27]
	v_mfma_f32_16x16x32_bf16 v[20:23], v[154:157], v[166:169], v[20:23]
	v_mfma_f32_16x16x32_bf16 v[16:19], v[154:157], v[182:185], v[16:19]
	v_mfma_f32_16x16x32_bf16 v[12:15], v[154:157], v[186:189], v[12:15]
	v_mfma_f32_16x16x32_bf16 v[32:35], v[154:157], v[190:193], v[32:35]
	v_mfma_f32_16x16x32_bf16 v[36:39], v[154:157], v[194:197], v[36:39]
	v_mfma_f32_16x16x32_bf16 v[8:11], v[154:157], v[202:205], v[8:11]
	global_load_dwordx4 v[154:157], v[76:77], off offset:256
	global_load_dwordx4 v[158:161], v[80:81], off offset:256
	global_load_dwordx4 v[162:165], v[82:83], off offset:256
	global_load_dwordx4 v[166:169], v[84:85], off offset:256
	global_load_dwordx4 v[182:185], v[86:87], off offset:256
	global_load_dwordx4 v[186:189], v[88:89], off offset:256
	global_load_dwordx4 v[190:193], v[90:91], off offset:256
	global_load_dwordx4 v[194:197], v[92:93], off offset:256
	global_load_dwordx4 v[202:205], v[78:79], off offset:256
	s_waitcnt vmcnt(18)
	v_mfma_f32_16x16x32_bf16 v[28:31], v[206:209], v[210:213], v[28:31]
	v_mfma_f32_16x16x32_bf16 v[24:27], v[206:209], v[214:217], v[24:27]
	v_mfma_f32_16x16x32_bf16 v[20:23], v[206:209], v[220:223], v[20:23]
	v_mfma_f32_16x16x32_bf16 v[16:19], v[206:209], v[224:227], v[16:19]
	v_mfma_f32_16x16x32_bf16 v[12:15], v[206:209], v[228:231], v[12:15]
	v_mfma_f32_16x16x32_bf16 v[32:35], v[206:209], v[232:235], v[32:35]
	v_mfma_f32_16x16x32_bf16 v[36:39], v[206:209], v[244:247], v[36:39]
	v_mfma_f32_16x16x32_bf16 v[8:11], v[206:209], v[248:251], v[8:11]
	global_load_dwordx4 v[206:209], v[76:77], off offset:320
	global_load_dwordx4 v[210:213], v[80:81], off offset:320
	global_load_dwordx4 v[214:217], v[82:83], off offset:320
	global_load_dwordx4 v[220:223], v[84:85], off offset:320
	global_load_dwordx4 v[224:227], v[86:87], off offset:320
	global_load_dwordx4 v[228:231], v[88:89], off offset:320
	global_load_dwordx4 v[232:235], v[90:91], off offset:320
	global_load_dwordx4 v[244:247], v[92:93], off offset:320
	global_load_dwordx4 v[248:251], v[78:79], off offset:320
	s_waitcnt vmcnt(18)
	v_mfma_f32_16x16x32_bf16 v[28:31], v[118:121], v[122:125], v[28:31]
	v_mfma_f32_16x16x32_bf16 v[24:27], v[118:121], v[126:129], v[24:27]
	v_mfma_f32_16x16x32_bf16 v[20:23], v[118:121], v[130:133], v[20:23]
	v_mfma_f32_16x16x32_bf16 v[16:19], v[118:121], v[134:137], v[16:19]
	v_mfma_f32_16x16x32_bf16 v[12:15], v[118:121], v[138:141], v[12:15]
	v_mfma_f32_16x16x32_bf16 v[32:35], v[118:121], v[142:145], v[32:35]
	v_mfma_f32_16x16x32_bf16 v[36:39], v[118:121], v[146:149], v[36:39]
	v_mfma_f32_16x16x32_bf16 v[8:11], v[118:121], v[150:153], v[8:11]
	global_load_dwordx4 v[118:121], v[76:77], off offset:384
	global_load_dwordx4 v[122:125], v[80:81], off offset:384
	global_load_dwordx4 v[126:129], v[82:83], off offset:384
	global_load_dwordx4 v[130:133], v[84:85], off offset:384
	global_load_dwordx4 v[134:137], v[86:87], off offset:384
	global_load_dwordx4 v[138:141], v[88:89], off offset:384
	global_load_dwordx4 v[142:145], v[90:91], off offset:384
	global_load_dwordx4 v[146:149], v[92:93], off offset:384
	global_load_dwordx4 v[150:153], v[78:79], off offset:384
	s_waitcnt vmcnt(18)
	v_mfma_f32_16x16x32_bf16 v[28:31], v[154:157], v[158:161], v[28:31]
	v_mfma_f32_16x16x32_bf16 v[24:27], v[154:157], v[162:165], v[24:27]
	v_mfma_f32_16x16x32_bf16 v[20:23], v[154:157], v[166:169], v[20:23]
	v_mfma_f32_16x16x32_bf16 v[16:19], v[154:157], v[182:185], v[16:19]
	v_mfma_f32_16x16x32_bf16 v[12:15], v[154:157], v[186:189], v[12:15]
	v_mfma_f32_16x16x32_bf16 v[32:35], v[154:157], v[190:193], v[32:35]
	v_mfma_f32_16x16x32_bf16 v[36:39], v[154:157], v[194:197], v[36:39]
	v_mfma_f32_16x16x32_bf16 v[8:11], v[154:157], v[202:205], v[8:11]
	global_load_dwordx4 v[154:157], v[76:77], off offset:448
	global_load_dwordx4 v[158:161], v[80:81], off offset:448
	global_load_dwordx4 v[162:165], v[82:83], off offset:448
	global_load_dwordx4 v[166:169], v[84:85], off offset:448
	global_load_dwordx4 v[182:185], v[86:87], off offset:448
	global_load_dwordx4 v[186:189], v[88:89], off offset:448
	global_load_dwordx4 v[190:193], v[90:91], off offset:448
	global_load_dwordx4 v[194:197], v[92:93], off offset:448
	global_load_dwordx4 v[202:205], v[78:79], off offset:448
	s_waitcnt vmcnt(18)
	v_mfma_f32_16x16x32_bf16 v[28:31], v[206:209], v[210:213], v[28:31]
	v_mfma_f32_16x16x32_bf16 v[24:27], v[206:209], v[214:217], v[24:27]
	v_mfma_f32_16x16x32_bf16 v[20:23], v[206:209], v[220:223], v[20:23]
	v_mfma_f32_16x16x32_bf16 v[16:19], v[206:209], v[224:227], v[16:19]
	v_mfma_f32_16x16x32_bf16 v[12:15], v[206:209], v[228:231], v[12:15]
	v_mfma_f32_16x16x32_bf16 v[32:35], v[206:209], v[232:235], v[32:35]
	v_mfma_f32_16x16x32_bf16 v[36:39], v[206:209], v[244:247], v[36:39]
	v_mfma_f32_16x16x32_bf16 v[8:11], v[206:209], v[248:251], v[8:11]
	global_load_dwordx4 v[206:209], v[76:77], off offset:512
	global_load_dwordx4 v[210:213], v[80:81], off offset:512
	global_load_dwordx4 v[214:217], v[82:83], off offset:512
	global_load_dwordx4 v[220:223], v[84:85], off offset:512
	global_load_dwordx4 v[224:227], v[86:87], off offset:512
	global_load_dwordx4 v[228:231], v[88:89], off offset:512
	global_load_dwordx4 v[232:235], v[90:91], off offset:512
	global_load_dwordx4 v[244:247], v[92:93], off offset:512
	global_load_dwordx4 v[248:251], v[78:79], off offset:512
	s_waitcnt vmcnt(18)
	v_mfma_f32_16x16x32_bf16 v[28:31], v[118:121], v[122:125], v[28:31]
	v_mfma_f32_16x16x32_bf16 v[24:27], v[118:121], v[126:129], v[24:27]
	v_mfma_f32_16x16x32_bf16 v[20:23], v[118:121], v[130:133], v[20:23]
	v_mfma_f32_16x16x32_bf16 v[16:19], v[118:121], v[134:137], v[16:19]
	v_mfma_f32_16x16x32_bf16 v[12:15], v[118:121], v[138:141], v[12:15]
	v_mfma_f32_16x16x32_bf16 v[32:35], v[118:121], v[142:145], v[32:35]
	v_mfma_f32_16x16x32_bf16 v[36:39], v[118:121], v[146:149], v[36:39]
	v_mfma_f32_16x16x32_bf16 v[8:11], v[118:121], v[150:153], v[8:11]
	global_load_dwordx4 v[118:121], v[76:77], off offset:576
	global_load_dwordx4 v[122:125], v[80:81], off offset:576
	global_load_dwordx4 v[126:129], v[82:83], off offset:576
	global_load_dwordx4 v[130:133], v[84:85], off offset:576
	global_load_dwordx4 v[134:137], v[86:87], off offset:576
	global_load_dwordx4 v[138:141], v[88:89], off offset:576
	global_load_dwordx4 v[142:145], v[90:91], off offset:576
	global_load_dwordx4 v[146:149], v[92:93], off offset:576
	global_load_dwordx4 v[150:153], v[78:79], off offset:576
	s_waitcnt vmcnt(18)
	v_mfma_f32_16x16x32_bf16 v[28:31], v[154:157], v[158:161], v[28:31]
	v_mfma_f32_16x16x32_bf16 v[24:27], v[154:157], v[162:165], v[24:27]
	v_mfma_f32_16x16x32_bf16 v[20:23], v[154:157], v[166:169], v[20:23]
	v_mfma_f32_16x16x32_bf16 v[16:19], v[154:157], v[182:185], v[16:19]
	v_mfma_f32_16x16x32_bf16 v[12:15], v[154:157], v[186:189], v[12:15]
	v_mfma_f32_16x16x32_bf16 v[32:35], v[154:157], v[190:193], v[32:35]
	v_mfma_f32_16x16x32_bf16 v[36:39], v[154:157], v[194:197], v[36:39]
	v_mfma_f32_16x16x32_bf16 v[8:11], v[154:157], v[202:205], v[8:11]
	global_load_dwordx4 v[154:157], v[76:77], off offset:640
	global_load_dwordx4 v[158:161], v[80:81], off offset:640
	global_load_dwordx4 v[162:165], v[82:83], off offset:640
	global_load_dwordx4 v[166:169], v[84:85], off offset:640
	global_load_dwordx4 v[182:185], v[86:87], off offset:640
	global_load_dwordx4 v[186:189], v[88:89], off offset:640
	global_load_dwordx4 v[190:193], v[90:91], off offset:640
	global_load_dwordx4 v[194:197], v[92:93], off offset:640
	global_load_dwordx4 v[202:205], v[78:79], off offset:640
	s_waitcnt vmcnt(18)
	v_mfma_f32_16x16x32_bf16 v[28:31], v[206:209], v[210:213], v[28:31]
	v_mfma_f32_16x16x32_bf16 v[24:27], v[206:209], v[214:217], v[24:27]
	v_mfma_f32_16x16x32_bf16 v[20:23], v[206:209], v[220:223], v[20:23]
	v_mfma_f32_16x16x32_bf16 v[16:19], v[206:209], v[224:227], v[16:19]
	v_mfma_f32_16x16x32_bf16 v[12:15], v[206:209], v[228:231], v[12:15]
	v_mfma_f32_16x16x32_bf16 v[32:35], v[206:209], v[232:235], v[32:35]
	v_mfma_f32_16x16x32_bf16 v[36:39], v[206:209], v[244:247], v[36:39]
	v_mfma_f32_16x16x32_bf16 v[8:11], v[206:209], v[248:251], v[8:11]
	global_load_dwordx4 v[206:209], v[76:77], off offset:704
	global_load_dwordx4 v[210:213], v[80:81], off offset:704
	global_load_dwordx4 v[214:217], v[82:83], off offset:704
	global_load_dwordx4 v[220:223], v[84:85], off offset:704
	global_load_dwordx4 v[224:227], v[86:87], off offset:704
	global_load_dwordx4 v[228:231], v[88:89], off offset:704
	global_load_dwordx4 v[232:235], v[90:91], off offset:704
	global_load_dwordx4 v[244:247], v[92:93], off offset:704
	global_load_dwordx4 v[248:251], v[78:79], off offset:704
	s_waitcnt vmcnt(18)
	v_mfma_f32_16x16x32_bf16 v[28:31], v[118:121], v[122:125], v[28:31]
	v_mfma_f32_16x16x32_bf16 v[24:27], v[118:121], v[126:129], v[24:27]
	v_mfma_f32_16x16x32_bf16 v[20:23], v[118:121], v[130:133], v[20:23]
	v_mfma_f32_16x16x32_bf16 v[16:19], v[118:121], v[134:137], v[16:19]
	v_mfma_f32_16x16x32_bf16 v[12:15], v[118:121], v[138:141], v[12:15]
	v_mfma_f32_16x16x32_bf16 v[32:35], v[118:121], v[142:145], v[32:35]
	v_mfma_f32_16x16x32_bf16 v[36:39], v[118:121], v[146:149], v[36:39]
	v_mfma_f32_16x16x32_bf16 v[8:11], v[118:121], v[150:153], v[8:11]
	global_load_dwordx4 v[118:121], v[76:77], off offset:768
	global_load_dwordx4 v[122:125], v[80:81], off offset:768
	global_load_dwordx4 v[126:129], v[82:83], off offset:768
	global_load_dwordx4 v[130:133], v[84:85], off offset:768
	global_load_dwordx4 v[134:137], v[86:87], off offset:768
	global_load_dwordx4 v[138:141], v[88:89], off offset:768
	global_load_dwordx4 v[142:145], v[90:91], off offset:768
	global_load_dwordx4 v[146:149], v[92:93], off offset:768
	global_load_dwordx4 v[150:153], v[78:79], off offset:768
	s_waitcnt vmcnt(18)
	v_mfma_f32_16x16x32_bf16 v[28:31], v[154:157], v[158:161], v[28:31]
	v_mfma_f32_16x16x32_bf16 v[24:27], v[154:157], v[162:165], v[24:27]
	v_mfma_f32_16x16x32_bf16 v[20:23], v[154:157], v[166:169], v[20:23]
	v_mfma_f32_16x16x32_bf16 v[16:19], v[154:157], v[182:185], v[16:19]
	v_mfma_f32_16x16x32_bf16 v[12:15], v[154:157], v[186:189], v[12:15]
	v_mfma_f32_16x16x32_bf16 v[32:35], v[154:157], v[190:193], v[32:35]
	v_mfma_f32_16x16x32_bf16 v[36:39], v[154:157], v[194:197], v[36:39]
	v_mfma_f32_16x16x32_bf16 v[8:11], v[154:157], v[202:205], v[8:11]
	global_load_dwordx4 v[154:157], v[76:77], off offset:832
	global_load_dwordx4 v[158:161], v[80:81], off offset:832
	global_load_dwordx4 v[162:165], v[82:83], off offset:832
	global_load_dwordx4 v[166:169], v[84:85], off offset:832
	global_load_dwordx4 v[182:185], v[86:87], off offset:832
	global_load_dwordx4 v[186:189], v[88:89], off offset:832
	global_load_dwordx4 v[190:193], v[90:91], off offset:832
	global_load_dwordx4 v[194:197], v[92:93], off offset:832
	global_load_dwordx4 v[202:205], v[78:79], off offset:832
	s_waitcnt vmcnt(18)
	v_mfma_f32_16x16x32_bf16 v[28:31], v[206:209], v[210:213], v[28:31]
	v_mfma_f32_16x16x32_bf16 v[24:27], v[206:209], v[214:217], v[24:27]
	v_mfma_f32_16x16x32_bf16 v[20:23], v[206:209], v[220:223], v[20:23]
	v_mfma_f32_16x16x32_bf16 v[16:19], v[206:209], v[224:227], v[16:19]
	v_mfma_f32_16x16x32_bf16 v[12:15], v[206:209], v[228:231], v[12:15]
	v_mfma_f32_16x16x32_bf16 v[32:35], v[206:209], v[232:235], v[32:35]
	v_mfma_f32_16x16x32_bf16 v[36:39], v[206:209], v[244:247], v[36:39]
	v_mfma_f32_16x16x32_bf16 v[8:11], v[206:209], v[248:251], v[8:11]
	global_load_dwordx4 v[206:209], v[76:77], off offset:896
	global_load_dwordx4 v[210:213], v[80:81], off offset:896
	global_load_dwordx4 v[214:217], v[82:83], off offset:896
	global_load_dwordx4 v[220:223], v[84:85], off offset:896
	global_load_dwordx4 v[224:227], v[86:87], off offset:896
	global_load_dwordx4 v[228:231], v[88:89], off offset:896
	global_load_dwordx4 v[232:235], v[90:91], off offset:896
	global_load_dwordx4 v[244:247], v[92:93], off offset:896
	global_load_dwordx4 v[248:251], v[78:79], off offset:896
	s_waitcnt vmcnt(18)
	v_mfma_f32_16x16x32_bf16 v[28:31], v[118:121], v[122:125], v[28:31]
	v_mfma_f32_16x16x32_bf16 v[24:27], v[118:121], v[126:129], v[24:27]
	v_mfma_f32_16x16x32_bf16 v[20:23], v[118:121], v[130:133], v[20:23]
	v_mfma_f32_16x16x32_bf16 v[16:19], v[118:121], v[134:137], v[16:19]
	v_mfma_f32_16x16x32_bf16 v[12:15], v[118:121], v[138:141], v[12:15]
	v_mfma_f32_16x16x32_bf16 v[32:35], v[118:121], v[142:145], v[32:35]
	v_mfma_f32_16x16x32_bf16 v[36:39], v[118:121], v[146:149], v[36:39]
	v_mfma_f32_16x16x32_bf16 v[8:11], v[118:121], v[150:153], v[8:11]
	global_load_dwordx4 v[118:121], v[76:77], off offset:960
	global_load_dwordx4 v[122:125], v[80:81], off offset:960
	global_load_dwordx4 v[126:129], v[82:83], off offset:960
	global_load_dwordx4 v[130:133], v[84:85], off offset:960
	global_load_dwordx4 v[134:137], v[86:87], off offset:960
	global_load_dwordx4 v[138:141], v[88:89], off offset:960
	global_load_dwordx4 v[142:145], v[90:91], off offset:960
	global_load_dwordx4 v[146:149], v[92:93], off offset:960
	global_load_dwordx4 v[150:153], v[78:79], off offset:960
	s_waitcnt vmcnt(18)
	v_mfma_f32_16x16x32_bf16 v[28:31], v[154:157], v[158:161], v[28:31]
	v_mfma_f32_16x16x32_bf16 v[24:27], v[154:157], v[162:165], v[24:27]
	v_mfma_f32_16x16x32_bf16 v[20:23], v[154:157], v[166:169], v[20:23]
	v_mfma_f32_16x16x32_bf16 v[16:19], v[154:157], v[182:185], v[16:19]
	v_mfma_f32_16x16x32_bf16 v[12:15], v[154:157], v[186:189], v[12:15]
	v_mfma_f32_16x16x32_bf16 v[32:35], v[154:157], v[190:193], v[32:35]
	v_mfma_f32_16x16x32_bf16 v[36:39], v[154:157], v[194:197], v[36:39]
	v_mfma_f32_16x16x32_bf16 v[8:11], v[154:157], v[202:205], v[8:11]
	s_waitcnt vmcnt(9)
	v_mfma_f32_16x16x32_bf16 v[28:31], v[206:209], v[210:213], v[28:31]
	v_mfma_f32_16x16x32_bf16 v[24:27], v[206:209], v[214:217], v[24:27]
	v_mfma_f32_16x16x32_bf16 v[20:23], v[206:209], v[220:223], v[20:23]
	v_mfma_f32_16x16x32_bf16 v[16:19], v[206:209], v[224:227], v[16:19]
	v_mfma_f32_16x16x32_bf16 v[12:15], v[206:209], v[228:231], v[12:15]
	v_mfma_f32_16x16x32_bf16 v[32:35], v[206:209], v[232:235], v[32:35]
	v_mfma_f32_16x16x32_bf16 v[36:39], v[206:209], v[244:247], v[36:39]
	v_mfma_f32_16x16x32_bf16 v[8:11], v[206:209], v[248:251], v[8:11]
	s_waitcnt vmcnt(0)
	v_mfma_f32_16x16x32_bf16 v[28:31], v[118:121], v[122:125], v[28:31]
	v_mfma_f32_16x16x32_bf16 v[24:27], v[118:121], v[126:129], v[24:27]
	v_mfma_f32_16x16x32_bf16 v[20:23], v[118:121], v[130:133], v[20:23]
	v_mfma_f32_16x16x32_bf16 v[16:19], v[118:121], v[134:137], v[16:19]
	v_mfma_f32_16x16x32_bf16 v[12:15], v[118:121], v[138:141], v[12:15]
	v_mfma_f32_16x16x32_bf16 v[32:35], v[118:121], v[142:145], v[32:35]
	v_mfma_f32_16x16x32_bf16 v[36:39], v[118:121], v[146:149], v[36:39]
	v_mfma_f32_16x16x32_bf16 v[8:11], v[118:121], v[150:153], v[8:11]
	s_nop 4
	s_waitcnt lgkmcnt(0)
	v_pk_add_f32 v[52:53], v[54:55], v[56:57]
	s_nop 0
	v_pk_mul_f32 v[52:53], v[52:53], s[6:7] op_sel_hi:[1,0]
	s_nop 0
	v_fma_f32 v49, -v52, v52, v53
	v_max_f32_e32 v49, 0, v49
	v_add_f32_e32 v49, 0x3727c5ac, v49
	v_mul_f32_e32 v53, 0x4b800000, v49
	v_cmp_gt_f32_e64 s[22:23], s14, v49
	s_nop 1
	v_cndmask_b32_e64 v49, v49, v53, s[22:23]
	v_rsq_f32_e32 v49, v49
	v_add_u32_e32 v53, s4, v64
	ds_write_b128 v53, v[28:31]
	ds_write_b128 v53, v[24:27] offset:1024
	ds_write_b128 v53, v[20:23] offset:2048
	ds_write_b128 v53, v[16:19] offset:3072
	ds_write_b128 v53, v[12:15] offset:4096
	ds_write_b128 v53, v[32:35] offset:5120
	ds_write_b128 v53, v[36:39] offset:6144
	ds_write_b128 v53, v[8:11] offset:7168
	v_add_u32_e32 v23, s12, v64
	s_waitcnt lgkmcnt(0)
	s_barrier
	ds_read_b128 v[8:11], v23
	ds_read_b128 v[12:15], v23 offset:8192
	v_mul_f32_e32 v16, 0x45800000, v49
	v_cndmask_b32_e64 v22, v49, v16, s[22:23]
	ds_read_b128 v[16:19], v23 offset:16384
	s_waitcnt lgkmcnt(2)
	v_pk_add_f32 v[10:11], v[10:11], 0 op_sel_hi:[1,0]
	v_pk_add_f32 v[20:21], v[8:9], 0 op_sel_hi:[1,0]
	s_waitcnt lgkmcnt(1)
	v_pk_add_f32 v[14:15], v[10:11], v[14:15]
	ds_read_b128 v[8:11], v23 offset:24576
	v_pk_add_f32 v[20:21], v[20:21], v[12:13]
	s_waitcnt lgkmcnt(1)
	v_pk_add_f32 v[18:19], v[14:15], v[18:19]
	ds_read_b128 v[12:15], v23 offset:32768
	v_pk_add_f32 v[16:17], v[20:21], v[16:17]
	s_waitcnt lgkmcnt(1)
	v_pk_add_f32 v[18:19], v[18:19], v[10:11]
	v_pk_add_f32 v[20:21], v[16:17], v[8:9]
	ds_read_b128 v[8:11], v23 offset:40960
	s_waitcnt lgkmcnt(1)
	v_pk_add_f32 v[24:25], v[18:19], v[14:15]
	ds_read_b128 v[14:17], v23 offset:49152
	v_pk_add_f32 v[12:13], v[20:21], v[12:13]
	ds_read_b128 v[18:21], v23 offset:57344
	s_waitcnt lgkmcnt(2)
	v_pk_add_f32 v[8:9], v[12:13], v[8:9]
	v_lshlrev_b32_e32 v12, 16, v60
	s_waitcnt lgkmcnt(1)
	v_pk_add_f32 v[8:9], v[8:9], v[14:15]
	v_and_b32_e32 v13, 0xffff0000, v60
	v_lshlrev_b32_e32 v14, 16, v61
	v_and_b32_e32 v15, 0xffff0000, v61
	v_pk_add_f32 v[10:11], v[24:25], v[10:11]
	v_sub_f32_e32 v13, v13, v52
	v_sub_f32_e32 v12, v12, v52
	v_sub_f32_e32 v15, v15, v52
	v_sub_f32_e32 v14, v14, v52
	v_pk_add_f32 v[10:11], v[10:11], v[16:17]
	v_pk_mul_f32 v[14:15], v[14:15], v[22:23] op_sel_hi:[1,0]
	v_pk_mul_f32 v[12:13], v[12:13], v[22:23] op_sel_hi:[1,0]
	s_waitcnt lgkmcnt(0)
	v_pk_add_f32 v[10:11], v[10:11], v[20:21]
	v_pk_add_f32 v[8:9], v[8:9], v[18:19]
	v_pk_fma_f32 v[0:1], v[0:1], v[12:13], v[4:5]
	v_pk_fma_f32 v[2:3], v[2:3], v[14:15], v[6:7]
	v_pk_fma_f32 v[6:7], v[0:1], s[70:71], v[8:9] op_sel_hi:[1,0,1]
	v_pk_fma_f32 v[4:5], v[2:3], s[70:71], v[10:11] op_sel_hi:[1,0,1]
	v_mul_f32_e32 v1, v6, v6
	v_mul_f32_e32 v3, v7, v7
	v_mul_f32_e32 v9, v4, v4
	v_mul_f32_e32 v11, v5, v5
	v_mov_b32_e32 v0, v6
	v_mov_b32_e32 v2, v7
	v_mov_b32_e32 v8, v4
	v_mov_b32_e32 v10, v5
	v_pk_add_f32 v[0:1], v[0:1], v[2:3]
	v_pk_add_f32 v[2:3], v[8:9], v[10:11]
	v_cvt_pk_bf16_f32 v6, v6, v7
	v_cvt_pk_bf16_f32 v7, v4, v5
	global_store_dwordx2 v[58:59], v[6:7], off
	v_pk_add_f32 v[0:1], v[0:1], v[2:3]
	ds_bpermute_b32 v2, v66, v0
	ds_bpermute_b32 v3, v66, v1
	s_waitcnt lgkmcnt(0)
	v_pk_add_f32 v[0:1], v[0:1], v[2:3]
	ds_bpermute_b32 v2, v67, v0
	ds_bpermute_b32 v3, v67, v1
	s_and_saveexec_b64 s[10:11], vcc
	s_cbranch_execz .LBB0_1373
	s_lshl_b32 s16, s13, 1
	s_ashr_i32 s17, s16, 31
	v_lshl_add_u64 v[4:5], s[16:17], 2, v[44:45]
	s_waitcnt lgkmcnt(0)
	v_pk_add_f32 v[0:1], v[0:1], v[2:3]
	global_store_dwordx2 v[4:5], v[0:1], off
	s_branch .LBB0_1373
